# attention P.V blocks: counted lgkmcnt waits keep 8 transposed LDS reads in flight instead of full drains (on top of LRU register rewrite)
# speedup vs baseline: 1.0343x; 1.0087x over previous
.LBB0_389:
	ds_read_b128 v[98:101], v214 offset:49152
	ds_read_b128 v[102:105], v214 offset:49280
	ds_read_b128 v[106:109], v214 offset:57344
	ds_read_b128 v[110:113], v214 offset:57472
	ds_read_b128 v[178:181], v215 offset:49152
	ds_read_b128 v[184:187], v215 offset:49280
	ds_read_b128 v[188:191], v215 offset:57344
	ds_read_b128 v[226:229], v215 offset:57472
	s_waitcnt lgkmcnt(7)
	v_mfma_f32_32x32x16_bf16 v[50:65], v[98:101], v[158:161], v[50:65]
	ds_read_b128 v[98:101], v216 offset:49152
	ds_read_b128 v[230:233], v216 offset:49280
	ds_read_b128 v[234:237], v216 offset:57344
	ds_read_b128 v[238:241], v216 offset:57472
	ds_read_b128 v[242:245], v217 offset:49152
	ds_read_b128 v[246:249], v217 offset:49280
	ds_read_b128 v[250:253], v217 offset:57344
	ds_read_b128 v[192:195], v217 offset:57472
	v_exp_f32_e32 v128, v128
	v_exp_f32_e32 v129, v129
	v_exp_f32_e32 v126, v126
	v_exp_f32_e32 v127, v127
	v_exp_f32_e32 v124, v124
	v_exp_f32_e32 v125, v125
	s_waitcnt lgkmcnt(11)
	v_mfma_f32_32x32x16_bf16 v[50:65], v[178:181], v[154:157], v[50:65]
	v_exp_f32_e32 v122, v122
	v_exp_f32_e32 v116, v116
	v_exp_f32_e32 v117, v117
	v_exp_f32_e32 v114, v114
	v_exp_f32_e32 v115, v115
	v_cvt_pk_bf16_f32 v178, v175, v177
	v_cvt_pk_bf16_f32 v179, v173, v176
	s_waitcnt lgkmcnt(7)
	v_mfma_f32_32x32x16_bf16 v[50:65], v[98:101], v[150:153], v[50:65]
	v_exp_f32_e32 v101, v118
	v_exp_f32_e32 v118, v119
	v_add_f32_e32 v119, 0, v175
	v_add_f32_e32 v119, v177, v119
	v_add_f32_e32 v119, v173, v119
	v_add_f32_e32 v119, v176, v119
	v_add_f32_e32 v119, v171, v119
	s_waitcnt lgkmcnt(3)
	v_mfma_f32_32x32x16_bf16 v[50:65], v[242:245], v[146:149], v[50:65]
	v_exp_f32_e32 v98, v123
	v_exp_f32_e32 v99, v120
	v_exp_f32_e32 v100, v121
	v_cvt_pk_bf16_f32 v180, v171, v174
	v_cvt_pk_bf16_f32 v181, v170, v172
	s_nop 0
	v_permlane32_swap_b32_e32 v178, v180
	v_mfma_f32_32x32x16_bf16 v[50:65], v[102:105], v[142:145], v[50:65]
	v_add_f32_e32 v102, v174, v119
	v_add_f32_e32 v102, v170, v102
	v_add_f32_e32 v102, v172, v102
	v_add_f32_e32 v102, v164, v102
	v_add_f32_e32 v102, v167, v102
	v_add_f32_e32 v102, v163, v102
	v_add_f32_e32 v102, v165, v102
	v_mfma_f32_32x32x16_bf16 v[50:65], v[184:187], v[138:141], v[50:65]
	v_add_f32_e32 v102, v162, v102
	v_add_f32_e32 v102, v169, v102
	v_add_f32_e32 v102, v166, v102
	v_add_f32_e32 v102, v168, v102
	v_add_f32_e32 v102, v128, v102
	v_add_f32_e32 v102, v129, v102
	v_add_f32_e32 v102, v126, v102
	v_mfma_f32_32x32x16_bf16 v[50:65], v[230:233], v[134:137], v[50:65]
	v_add_f32_e32 v102, v127, v102
	v_add_f32_e32 v102, v124, v102
	v_add_f32_e32 v102, v125, v102
	v_add_f32_e32 v102, v122, v102
	v_add_f32_e32 v102, v98, v102
	v_add_f32_e32 v102, v99, v102
	v_add_f32_e32 v102, v100, v102
	s_waitcnt lgkmcnt(2)
	v_mfma_f32_32x32x16_bf16 v[50:65], v[246:249], v[130:133], v[50:65]
	v_add_f32_e32 v102, v101, v102
	v_add_f32_e32 v102, v118, v102
	v_add_f32_e32 v102, v116, v102
	v_add_f32_e32 v102, v117, v102
	v_add_f32_e32 v102, v114, v102
	v_add_f32_e32 v223, v115, v102
	v_mov_b32_e32 v224, v223
	s_nop 1
	v_permlane32_swap_b32_e32 v223, v224
	v_cvt_pk_bf16_f32 v184, v164, v167
	v_cvt_pk_bf16_f32 v185, v163, v165
	v_cvt_pk_bf16_f32 v186, v162, v169
	v_cvt_pk_bf16_f32 v187, v166, v168
	v_cvt_pk_bf16_f32 v230, v128, v129
	v_cvt_pk_bf16_f32 v231, v126, v127
	v_cvt_pk_bf16_f32 v232, v124, v125
	v_cvt_pk_bf16_f32 v233, v122, v98
	v_cvt_pk_bf16_f32 v242, v99, v100
	v_cvt_pk_bf16_f32 v243, v101, v118
	v_cvt_pk_bf16_f32 v244, v116, v117
	v_cvt_pk_bf16_f32 v245, v114, v115
	v_permlane32_swap_b32_e32 v179, v181
	v_permlane32_swap_b32_e32 v184, v186
	v_permlane32_swap_b32_e32 v185, v187
	v_permlane32_swap_b32_e32 v230, v232
	v_permlane32_swap_b32_e32 v231, v233
	v_permlane32_swap_b32_e32 v242, v244
	v_permlane32_swap_b32_e32 v243, v245
	v_mfma_f32_32x32x16_bf16 v[82:97], v[106:109], v[158:161], v[82:97]
	s_add_i32 s6, s38, 63
	v_mfma_f32_32x32x16_bf16 v[82:97], v[188:191], v[154:157], v[82:97]
	v_mfma_f32_32x32x16_bf16 v[82:97], v[234:237], v[150:153], v[82:97]
	s_waitcnt lgkmcnt(1)
	v_mfma_f32_32x32x16_bf16 v[82:97], v[250:253], v[146:149], v[82:97]
	v_mfma_f32_32x32x16_bf16 v[82:97], v[110:113], v[142:145], v[82:97]
	v_add_u32_e32 v110, 0x100, v221
	global_load_dwordx4 v[114:117], v110, s[52:53]
	global_load_dwordx4 v[118:121], v110, s[52:53] offset:32
	global_load_dwordx4 v[98:101], v110, s[52:53] offset:128
	global_load_dwordx4 v[102:105], v110, s[52:53] offset:160
	global_load_dwordx4 v[122:125], v110, s[52:53] offset:64
	global_load_dwordx4 v[126:129], v110, s[52:53] offset:96
	global_load_dwordx4 v[106:109], v110, s[52:53] offset:192
	s_nop 0
	global_load_dwordx4 v[110:113], v110, s[52:53] offset:224
	v_mfma_f32_32x32x16_bf16 v[82:97], v[226:229], v[138:141], v[82:97]
	v_mfma_f32_32x32x16_bf16 v[82:97], v[238:241], v[134:137], v[82:97]
	s_waitcnt lgkmcnt(0)
	v_mfma_f32_32x32x16_bf16 v[82:97], v[192:195], v[130:133], v[82:97]
	v_add_u32_e32 v229, s38, v201
	v_subrev_u32_e32 v162, 64, v229
	v_subrev_u32_e32 v164, 32, v229
	v_ashrrev_i32_e32 v163, 31, v162
	v_ashrrev_i32_e32 v165, 31, v164
	v_lshlrev_b64 v[170:171], 8, v[162:163]
	v_lshlrev_b64 v[172:173], 8, v[164:165]
	v_lshl_add_u64 v[162:163], v[196:197], 0, v[170:171]
	v_lshl_add_u64 v[166:167], v[196:197], 0, v[172:173]
	v_lshl_add_u64 v[170:171], v[198:199], 0, v[170:171]
	v_lshl_add_u64 v[174:175], v[198:199], 0, v[172:173]
	global_load_dwordx4 v[162:165], v[162:163], off
	s_nop 0
	global_load_dwordx4 v[166:169], v[166:167], off
	s_nop 0
	global_load_dwordx4 v[170:173], v[170:171], off
	s_nop 0
	global_load_dwordx4 v[174:177], v[174:175], off
	ds_read_b64_tr_b16 v[188:189], v209 offset:0
	ds_read_b64_tr_b16 v[190:191], v209 offset:0x800
	ds_read_b64_tr_b16 v[192:193], v209 offset:0x1000
	ds_read_b64_tr_b16 v[194:195], v209 offset:0x1800
	ds_read_b64_tr_b16 v[234:235], v209 offset:0x2000
	ds_read_b64_tr_b16 v[236:237], v209 offset:0x2800
	ds_read_b64_tr_b16 v[238:239], v209 offset:0x3000
	ds_read_b64_tr_b16 v[240:241], v209 offset:0x3800
	s_nop 0
	s_waitcnt lgkmcnt(6)
	v_mfma_f32_32x32x16_bf16 v[66:81], v[178:181], v[188:191], v[66:81]
	ds_read_b64_tr_b16 v[188:189], v209 offset:0x200
	ds_read_b64_tr_b16 v[190:191], v209 offset:0xa00
	s_waitcnt lgkmcnt(6)
	v_mfma_f32_32x32x16_bf16 v[66:81], v[184:187], v[192:195], v[66:81]
	ds_read_b64_tr_b16 v[192:193], v209 offset:0x1200
	ds_read_b64_tr_b16 v[194:195], v209 offset:0x1a00
	s_waitcnt lgkmcnt(6)
	v_mfma_f32_32x32x16_bf16 v[66:81], v[230:233], v[234:237], v[66:81]
	ds_read_b64_tr_b16 v[234:235], v209 offset:0x2200
	ds_read_b64_tr_b16 v[236:237], v209 offset:0x2a00
	ds_read_b64_tr_b16 v[246:247], v209 offset:0x3200
	ds_read_b64_tr_b16 v[248:249], v209 offset:0x3a00
	s_waitcnt lgkmcnt(8)
	v_mfma_f32_32x32x16_bf16 v[66:81], v[242:245], v[238:241], v[66:81]
	s_waitcnt lgkmcnt(6)
	v_mfma_f32_32x32x16_bf16 v[34:49], v[178:181], v[188:191], v[34:49]
	ds_read_b64_tr_b16 v[188:189], v209 offset:0x400
	ds_read_b64_tr_b16 v[190:191], v209 offset:0xc00
	s_waitcnt lgkmcnt(6)
	v_mfma_f32_32x32x16_bf16 v[34:49], v[184:187], v[192:195], v[34:49]
	ds_read_b64_tr_b16 v[192:193], v209 offset:0x1400
	ds_read_b64_tr_b16 v[194:195], v209 offset:0x1c00
	s_waitcnt lgkmcnt(6)
	v_mfma_f32_32x32x16_bf16 v[34:49], v[230:233], v[234:237], v[34:49]
	ds_read_b64_tr_b16 v[234:235], v209 offset:0x2400
	ds_read_b64_tr_b16 v[236:237], v209 offset:0x2c00
	ds_read_b64_tr_b16 v[238:239], v209 offset:0x3400
	ds_read_b64_tr_b16 v[240:241], v209 offset:0x3c00
	s_waitcnt lgkmcnt(8)
	v_mfma_f32_32x32x16_bf16 v[34:49], v[242:245], v[246:249], v[34:49]
	s_waitcnt lgkmcnt(6)
	v_mfma_f32_32x32x16_bf16 v[18:33], v[178:181], v[188:191], v[18:33]
	ds_read_b64_tr_b16 v[188:189], v209 offset:0x600
	ds_read_b64_tr_b16 v[190:191], v209 offset:0xe00
	s_waitcnt lgkmcnt(6)
	v_mfma_f32_32x32x16_bf16 v[18:33], v[184:187], v[192:195], v[18:33]
	ds_read_b64_tr_b16 v[192:193], v209 offset:0x1600
	ds_read_b64_tr_b16 v[194:195], v209 offset:0x1e00
	s_waitcnt lgkmcnt(6)
	v_mfma_f32_32x32x16_bf16 v[18:33], v[230:233], v[234:237], v[18:33]
	ds_read_b64_tr_b16 v[234:235], v209 offset:0x2600
	ds_read_b64_tr_b16 v[236:237], v209 offset:0x2e00
	ds_read_b64_tr_b16 v[246:247], v209 offset:0x3600
	ds_read_b64_tr_b16 v[248:249], v209 offset:0x3e00
	s_waitcnt lgkmcnt(8)
	v_mfma_f32_32x32x16_bf16 v[18:33], v[242:245], v[238:241], v[18:33]
	s_waitcnt lgkmcnt(6)
	v_mfma_f32_32x32x16_bf16 v[2:17], v[178:181], v[188:191], v[2:17]
	s_cmp_le_i32 s6, s1
	s_cselect_b64 s[6:7], -1, 0
	s_cmp_gt_i32 s38, s8
	s_cselect_b64 s[54:55], -1, 0
	s_and_b64 s[6:7], s[6:7], s[54:55]
	s_and_b64 vcc, exec, s[6:7]
	s_waitcnt lgkmcnt(4)
	v_mfma_f32_32x32x16_bf16 v[2:17], v[184:187], v[192:195], v[2:17]
	s_waitcnt lgkmcnt(2)
	v_mfma_f32_32x32x16_bf16 v[2:17], v[230:233], v[234:237], v[2:17]
	s_waitcnt lgkmcnt(0)
	v_mfma_f32_32x32x16_bf16 v[2:17], v[242:245], v[246:249], v[2:17]
	s_cbranch_vccnz .LBB0_391
	v_subrev_u32_e32 v178, 64, v222
	v_cmp_gt_u32_e32 vcc, s11, v178
	v_add_u32_e32 v178, 0xffffefa0, v222
	s_nop 0
	v_cndmask_b32_e32 v50, v202, v50, vcc
	v_cmp_lt_u32_e32 vcc, s68, v178
	v_add_u32_e32 v178, 0xffffefbf, v222
	s_nop 0
	v_cndmask_b32_e32 v82, v202, v82, vcc
	v_cmp_lt_u32_e32 vcc, s68, v178
	v_add_u32_e32 v178, 0xffffef9f, v222
	s_nop 0
	v_cndmask_b32_e32 v51, v202, v51, vcc
	v_cmp_lt_u32_e32 vcc, s68, v178
	v_add_u32_e32 v178, 0xffffefbe, v222
	s_nop 0
	v_cndmask_b32_e32 v83, v202, v83, vcc
	v_cmp_lt_u32_e32 vcc, s68, v178
	v_add_u32_e32 v178, 0xffffef9e, v222
	s_nop 0
	v_cndmask_b32_e32 v52, v202, v52, vcc
	v_cmp_lt_u32_e32 vcc, s68, v178
	v_add_u32_e32 v178, 0xffffefbd, v222
	s_nop 0
	v_cndmask_b32_e32 v84, v202, v84, vcc
	v_cmp_lt_u32_e32 vcc, s68, v178
	v_add_u32_e32 v178, 0xffffef9d, v222
	s_nop 0
	v_cndmask_b32_e32 v53, v202, v53, vcc
	v_cmp_lt_u32_e32 vcc, s68, v178
	v_add_u32_e32 v178, 0xffffefb8, v222
	s_nop 0
	v_cndmask_b32_e32 v85, v202, v85, vcc
	v_cmp_lt_u32_e32 vcc, s68, v178
	v_add_u32_e32 v178, 0xffffef98, v222
	s_nop 0
	v_cndmask_b32_e32 v54, v202, v54, vcc
	v_cmp_lt_u32_e32 vcc, s68, v178
	v_add_u32_e32 v178, 0xffffefb7, v222
	s_nop 0
	v_cndmask_b32_e32 v86, v202, v86, vcc
	v_cmp_lt_u32_e32 vcc, s68, v178
	v_add_u32_e32 v178, 0xffffef97, v222
	s_nop 0
	v_cndmask_b32_e32 v55, v202, v55, vcc
	v_cmp_lt_u32_e32 vcc, s68, v178
	v_add_u32_e32 v178, 0xffffefb6, v222
	s_nop 0
	v_cndmask_b32_e32 v87, v202, v87, vcc
	v_cmp_lt_u32_e32 vcc, s68, v178
	v_add_u32_e32 v178, 0xffffef96, v222
	s_nop 0
	v_cndmask_b32_e32 v56, v202, v56, vcc
	v_cmp_lt_u32_e32 vcc, s68, v178
	v_add_u32_e32 v178, 0xffffefb5, v222
	s_nop 0
	v_cndmask_b32_e32 v88, v202, v88, vcc
	v_cmp_lt_u32_e32 vcc, s68, v178
	v_add_u32_e32 v178, 0xffffef95, v222
	s_nop 0
	v_cndmask_b32_e32 v57, v202, v57, vcc
	v_cmp_lt_u32_e32 vcc, s68, v178
	v_add_u32_e32 v178, 0xffffefb0, v222
	s_nop 0
	v_cndmask_b32_e32 v89, v202, v89, vcc
	v_cmp_lt_u32_e32 vcc, s68, v178
	v_add_u32_e32 v178, 0xffffef90, v222
	s_nop 0
	v_cndmask_b32_e32 v58, v202, v58, vcc
	v_cmp_lt_u32_e32 vcc, s68, v178
	v_add_u32_e32 v178, 0xffffefaf, v222
	s_nop 0
	v_cndmask_b32_e32 v90, v202, v90, vcc
	v_cmp_lt_u32_e32 vcc, s68, v178
	v_add_u32_e32 v178, 0xffffef8f, v222
	s_nop 0
	v_cndmask_b32_e32 v59, v202, v59, vcc
	v_cmp_lt_u32_e32 vcc, s68, v178
	v_add_u32_e32 v178, 0xffffefae, v222
	s_nop 0
	v_cndmask_b32_e32 v91, v202, v91, vcc
	v_cmp_lt_u32_e32 vcc, s68, v178
	v_add_u32_e32 v178, 0xffffef8e, v222
	s_nop 0
	v_cndmask_b32_e32 v60, v202, v60, vcc
	v_cmp_lt_u32_e32 vcc, s68, v178
	v_add_u32_e32 v178, 0xffffefad, v222
	s_nop 0
	v_cndmask_b32_e32 v92, v202, v92, vcc
	v_cmp_lt_u32_e32 vcc, s68, v178
	v_add_u32_e32 v178, 0xffffef8d, v222
	s_nop 0
	v_cndmask_b32_e32 v61, v202, v61, vcc
	v_cmp_lt_u32_e32 vcc, s68, v178
	v_add_u32_e32 v178, 0xffffefa8, v222
	s_nop 0
	v_cndmask_b32_e32 v93, v202, v93, vcc
	v_cmp_lt_u32_e32 vcc, s68, v178
	v_add_u32_e32 v178, 0xffffef88, v222
	s_nop 0
	v_cndmask_b32_e32 v62, v202, v62, vcc
	v_cmp_lt_u32_e32 vcc, s68, v178
	v_add_u32_e32 v178, 0xffffefa7, v222
	s_nop 0
	v_cndmask_b32_e32 v94, v202, v94, vcc
	v_cmp_lt_u32_e32 vcc, s68, v178
	v_add_u32_e32 v178, 0xffffef87, v222
	s_nop 0
	v_cndmask_b32_e32 v63, v202, v63, vcc
	v_cmp_lt_u32_e32 vcc, s68, v178
	v_add_u32_e32 v178, 0xffffefa6, v222
	s_nop 0
	v_cndmask_b32_e32 v95, v202, v95, vcc
	v_cmp_lt_u32_e32 vcc, s68, v178
	v_add_u32_e32 v178, 0xffffef86, v222
	s_nop 0
	v_cndmask_b32_e32 v64, v202, v64, vcc
	v_cmp_lt_u32_e32 vcc, s68, v178
	v_add_u32_e32 v178, 0xffffefa5, v222
	s_nop 0
	v_cndmask_b32_e32 v96, v202, v96, vcc
	v_cmp_lt_u32_e32 vcc, s68, v178
	v_add_u32_e32 v178, 0xffffef85, v222
	s_nop 0
	v_cndmask_b32_e32 v65, v202, v65, vcc
	v_cmp_lt_u32_e32 vcc, s68, v178
	s_nop 1
	v_cndmask_b32_e32 v97, v202, v97, vcc

.LBB0_397:
	ds_read_b64_tr_b16 v[230:231], v209 offset:0x4000
	ds_read_b64_tr_b16 v[232:233], v209 offset:0x4800
	ds_read_b64_tr_b16 v[234:235], v209 offset:0x5000
	ds_read_b64_tr_b16 v[236:237], v209 offset:0x5800
	ds_read_b64_tr_b16 v[238:239], v209 offset:0x6000
	ds_read_b64_tr_b16 v[240:241], v209 offset:0x6800
	ds_read_b64_tr_b16 v[242:243], v209 offset:0x7000
	ds_read_b64_tr_b16 v[244:245], v209 offset:0x7800
	s_add_i32 s6, s38, -1
	s_sub_i32 s39, s38, 64
	s_waitcnt lgkmcnt(6)
	v_mfma_f32_32x32x16_bf16 v[66:81], v[178:181], v[230:233], v[66:81]
	ds_read_b64_tr_b16 v[230:231], v209 offset:0x4200
	ds_read_b64_tr_b16 v[232:233], v209 offset:0x4a00
	s_waitcnt lgkmcnt(6)
	v_mfma_f32_32x32x16_bf16 v[66:81], v[182:185], v[234:237], v[66:81]
	ds_read_b64_tr_b16 v[234:235], v209 offset:0x5200
	ds_read_b64_tr_b16 v[236:237], v209 offset:0x5a00
	s_waitcnt lgkmcnt(6)
	v_mfma_f32_32x32x16_bf16 v[66:81], v[186:189], v[238:241], v[66:81]
	ds_read_b64_tr_b16 v[238:239], v209 offset:0x6200
	ds_read_b64_tr_b16 v[240:241], v209 offset:0x6a00
	ds_read_b64_tr_b16 v[246:247], v209 offset:0x7200
	ds_read_b64_tr_b16 v[248:249], v209 offset:0x7a00
	s_waitcnt lgkmcnt(8)
	v_mfma_f32_32x32x16_bf16 v[66:81], v[190:193], v[242:245], v[66:81]
	s_waitcnt lgkmcnt(6)
	v_mfma_f32_32x32x16_bf16 v[34:49], v[178:181], v[230:233], v[34:49]
	ds_read_b64_tr_b16 v[230:231], v209 offset:0x4400
	ds_read_b64_tr_b16 v[232:233], v209 offset:0x4c00
	s_waitcnt lgkmcnt(6)
	v_mfma_f32_32x32x16_bf16 v[34:49], v[182:185], v[234:237], v[34:49]
	ds_read_b64_tr_b16 v[234:235], v209 offset:0x5400
	ds_read_b64_tr_b16 v[236:237], v209 offset:0x5c00
	s_waitcnt lgkmcnt(6)
	v_mfma_f32_32x32x16_bf16 v[34:49], v[186:189], v[238:241], v[34:49]
	ds_read_b64_tr_b16 v[238:239], v209 offset:0x6400
	ds_read_b64_tr_b16 v[240:241], v209 offset:0x6c00
	ds_read_b64_tr_b16 v[242:243], v209 offset:0x7400
	ds_read_b64_tr_b16 v[244:245], v209 offset:0x7c00
	s_waitcnt lgkmcnt(8)
	v_mfma_f32_32x32x16_bf16 v[34:49], v[190:193], v[246:249], v[34:49]
	s_waitcnt lgkmcnt(6)
	v_mfma_f32_32x32x16_bf16 v[18:33], v[178:181], v[230:233], v[18:33]
	ds_read_b64_tr_b16 v[230:231], v209 offset:0x4600
	ds_read_b64_tr_b16 v[232:233], v209 offset:0x4e00
	s_waitcnt lgkmcnt(6)
	v_mfma_f32_32x32x16_bf16 v[18:33], v[182:185], v[234:237], v[18:33]
	ds_read_b64_tr_b16 v[234:235], v209 offset:0x5600
	ds_read_b64_tr_b16 v[236:237], v209 offset:0x5e00
	s_waitcnt lgkmcnt(6)
	v_mfma_f32_32x32x16_bf16 v[18:33], v[186:189], v[238:241], v[18:33]
	ds_read_b64_tr_b16 v[238:239], v209 offset:0x6600
	ds_read_b64_tr_b16 v[240:241], v209 offset:0x6e00
	ds_read_b64_tr_b16 v[246:247], v209 offset:0x7600
	ds_read_b64_tr_b16 v[248:249], v209 offset:0x7e00
	s_waitcnt lgkmcnt(8)
	v_mfma_f32_32x32x16_bf16 v[18:33], v[190:193], v[242:245], v[18:33]
	s_waitcnt lgkmcnt(6)
	v_mfma_f32_32x32x16_bf16 v[2:17], v[178:181], v[230:233], v[2:17]
	s_cmp_le_i32 s6, s1
	s_cselect_b64 s[6:7], -1, 0
	s_cmp_gt_i32 s39, s8
	s_cselect_b64 s[56:57], -1, 0
	s_and_b64 s[6:7], s[6:7], s[56:57]
	s_and_b64 vcc, exec, s[6:7]
	s_waitcnt lgkmcnt(4)
	v_mfma_f32_32x32x16_bf16 v[2:17], v[182:185], v[234:237], v[2:17]
	s_waitcnt lgkmcnt(2)
	v_mfma_f32_32x32x16_bf16 v[2:17], v[186:189], v[238:241], v[2:17]
	s_waitcnt lgkmcnt(0)
	v_mfma_f32_32x32x16_bf16 v[2:17], v[190:193], v[246:249], v[2:17]
	s_cbranch_vccnz .LBB0_399
	v_cmp_gt_u32_e32 vcc, s11, v222
	v_add_u32_e32 v178, 0xffffefe0, v222
	s_nop 0
	v_cndmask_b32_e32 v114, v202, v114, vcc
	v_cmp_lt_u32_e32 vcc, s68, v178
	v_add_u32_e32 v178, 0xffffefff, v222
	s_nop 0
	v_cndmask_b32_e32 v98, v202, v98, vcc
	v_cmp_lt_u32_e32 vcc, s68, v178
	v_add_u32_e32 v178, 0xffffefdf, v222
	s_nop 0
	v_cndmask_b32_e32 v115, v202, v115, vcc
	v_cmp_lt_u32_e32 vcc, s68, v178
	v_add_u32_e32 v178, 0xffffeffe, v222
	s_nop 0
	v_cndmask_b32_e32 v99, v202, v99, vcc
	v_cmp_lt_u32_e32 vcc, s68, v178
	v_add_u32_e32 v178, 0xffffefde, v222
	s_nop 0
	v_cndmask_b32_e32 v116, v202, v116, vcc
	v_cmp_lt_u32_e32 vcc, s68, v178
	v_add_u32_e32 v178, 0xffffeffd, v222
	s_nop 0
	v_cndmask_b32_e32 v100, v202, v100, vcc
	v_cmp_lt_u32_e32 vcc, s68, v178
	v_add_u32_e32 v178, 0xffffefdd, v222
	s_nop 0
	v_cndmask_b32_e32 v117, v202, v117, vcc
	v_cmp_lt_u32_e32 vcc, s68, v178
	v_add_u32_e32 v178, 0xffffeff8, v222
	s_nop 0
	v_cndmask_b32_e32 v101, v202, v101, vcc
	v_cmp_lt_u32_e32 vcc, s68, v178
	v_add_u32_e32 v178, 0xffffefd8, v222
	s_nop 0
	v_cndmask_b32_e32 v118, v202, v118, vcc
	v_cmp_lt_u32_e32 vcc, s68, v178
	v_add_u32_e32 v178, 0xffffeff7, v222
	s_nop 0
	v_cndmask_b32_e32 v102, v202, v102, vcc
	v_cmp_lt_u32_e32 vcc, s68, v178
	v_add_u32_e32 v178, 0xffffefd7, v222
	s_nop 0
	v_cndmask_b32_e32 v119, v202, v119, vcc
	v_cmp_lt_u32_e32 vcc, s68, v178
	v_add_u32_e32 v178, 0xffffeff6, v222
	s_nop 0
	v_cndmask_b32_e32 v103, v202, v103, vcc
	v_cmp_lt_u32_e32 vcc, s68, v178
	v_add_u32_e32 v178, 0xffffefd6, v222
	s_nop 0
	v_cndmask_b32_e32 v120, v202, v120, vcc
	v_cmp_lt_u32_e32 vcc, s68, v178
	v_add_u32_e32 v178, 0xffffeff5, v222
	s_nop 0
	v_cndmask_b32_e32 v104, v202, v104, vcc
	v_cmp_lt_u32_e32 vcc, s68, v178
	v_add_u32_e32 v178, 0xffffefd5, v222
	s_nop 0
	v_cndmask_b32_e32 v121, v202, v121, vcc
	v_cmp_lt_u32_e32 vcc, s68, v178
	v_add_u32_e32 v178, 0xffffeff0, v222
	s_nop 0
	v_cndmask_b32_e32 v105, v202, v105, vcc
	v_cmp_lt_u32_e32 vcc, s68, v178
	v_add_u32_e32 v178, 0xffffefd0, v222
	s_nop 0
	v_cndmask_b32_e32 v122, v202, v122, vcc
	v_cmp_lt_u32_e32 vcc, s68, v178
	v_add_u32_e32 v178, 0xffffefef, v222
	s_nop 0
	v_cndmask_b32_e32 v106, v202, v106, vcc
	v_cmp_lt_u32_e32 vcc, s68, v178
	v_add_u32_e32 v178, 0xffffefcf, v222
	s_nop 0
	v_cndmask_b32_e32 v123, v202, v123, vcc
	v_cmp_lt_u32_e32 vcc, s68, v178
	v_add_u32_e32 v178, 0xffffefee, v222
	s_nop 0
	v_cndmask_b32_e32 v107, v202, v107, vcc
	v_cmp_lt_u32_e32 vcc, s68, v178
	v_add_u32_e32 v178, 0xffffefce, v222
	s_nop 0
	v_cndmask_b32_e32 v124, v202, v124, vcc
	v_cmp_lt_u32_e32 vcc, s68, v178
	v_add_u32_e32 v178, 0xffffefed, v222
	s_nop 0
	v_cndmask_b32_e32 v108, v202, v108, vcc
	v_cmp_lt_u32_e32 vcc, s68, v178
	v_add_u32_e32 v178, 0xffffefcd, v222
	s_nop 0
	v_cndmask_b32_e32 v125, v202, v125, vcc
	v_cmp_lt_u32_e32 vcc, s68, v178
	v_add_u32_e32 v178, 0xffffefe8, v222
	s_nop 0
	v_cndmask_b32_e32 v109, v202, v109, vcc
	v_cmp_lt_u32_e32 vcc, s68, v178
	v_add_u32_e32 v178, 0xffffefc8, v222
	s_nop 0
	v_cndmask_b32_e32 v126, v202, v126, vcc
	v_cmp_lt_u32_e32 vcc, s68, v178
	v_add_u32_e32 v178, 0xffffefe7, v222
	s_nop 0
	v_cndmask_b32_e32 v110, v202, v110, vcc
	v_cmp_lt_u32_e32 vcc, s68, v178
	v_add_u32_e32 v178, 0xffffefc7, v222
	s_nop 0
	v_cndmask_b32_e32 v127, v202, v127, vcc
	v_cmp_lt_u32_e32 vcc, s68, v178
	v_add_u32_e32 v178, 0xffffefe6, v222
	s_nop 0
	v_cndmask_b32_e32 v111, v202, v111, vcc
	v_cmp_lt_u32_e32 vcc, s68, v178
	v_add_u32_e32 v178, 0xffffefc6, v222
	s_nop 0
	v_cndmask_b32_e32 v128, v202, v128, vcc
	v_cmp_lt_u32_e32 vcc, s68, v178
	v_add_u32_e32 v178, 0xffffefe5, v222
	s_nop 0
	v_cndmask_b32_e32 v112, v202, v112, vcc
	v_cmp_lt_u32_e32 vcc, s68, v178
	v_add_u32_e32 v178, 0xffffefc5, v222
	s_nop 0
	v_cndmask_b32_e32 v129, v202, v129, vcc
	v_cmp_lt_u32_e32 vcc, s68, v178
	s_nop 1
	v_cndmask_b32_e32 v113, v202, v113, vcc
